# weight-conversion filler items of layer l+1 split over both halves of layer l (256 per P4 instead of 512 in half 0)
# speedup vs baseline: 1.0074x; 1.0011x over previous
.LBB0_655:
	s_or_b64 exec, exec, s[0:1]
	v_readlane_b32 s0, v234, 30
	v_readlane_b32 s1, v234, 62
	s_or_b32 s34, s1, s0
	s_lshl_b64 s[0:1], s[34:35], 2
	v_readlane_b32 s12, v237, 8
	v_readlane_b32 s13, v237, 9
	s_add_u32 s44, s12, s0
	s_addc_u32 s45, s13, s1
	v_readlane_b32 s0, v234, 31
	v_readlane_b32 s12, v234, 63
	v_readlane_b32 s1, v234, 32
	v_readlane_b32 s13, v233, 0
	s_nop 0
	s_and_b64 s[0:1], s[0:1], exec
	s_movk_i32 s0, 0x520
	s_cselect_b32 s68, s0, 0x420
	s_mov_b64 s[46:47], 0
	s_mov_b32 s0, 0
	s_cmp_lg_u32 s26, 0x200
	s_cbranch_scc1 .Lp4s_set
	s_and_b32 s1, s89, 0x1e0
	s_cmp_eq_u32 s1, 0x100
	s_cbranch_scc1 .LBB0_945
	s_cmp_lg_u32 s1, 0
	s_cbranch_scc1 .Lp4s_set
	s_add_u32 s0, s89, 1

.LBB0_663:
	s_or_b64 exec, exec, s[0:1]
	v_mov_b32_e32 v181, v200
	s_waitcnt lgkmcnt(0)
	s_barrier
	flat_load_dword v104, v[180:181] sc0 sc1
	s_waitcnt vmcnt(0)
	s_mov_b64 s[0:1], -1
	s_waitcnt lgkmcnt(0)
	v_cmp_gt_i32_e32 vcc, s68, v104
	s_and_saveexec_b64 s[48:49], vcc
	s_cbranch_execz .LBB0_658
	v_cmp_lt_i32_e32 vcc, 31, v104
	s_and_saveexec_b64 s[0:1], vcc
	s_xor_b64 s[50:51], exec, s[0:1]
	s_cbranch_execz .LBB0_872
	s_movk_i32 s0, 0x41f
	v_cmp_lt_u32_e32 vcc, s0, v104
	s_and_saveexec_b64 s[0:1], vcc
	s_xor_b64 s[42:43], exec, s[0:1]
	s_cbranch_execz .LBB0_853
	v_readlane_b32 s0, v234, 62
	s_nop 3
	s_lshl_b32 s0, s0, 8
	v_add_u32_e32 v104, s0, v104
	v_mov_b32_e32 v0, v178
	s_movk_i32 s0, 0x104
	v_and_b32_e32 v2, 63, v0
	v_ashrrev_i32_e32 v10, 6, v0
	v_mul_u32_u24_e32 v0, 0x104, v2
	v_lshl_add_u32 v11, v10, 2, v0
	v_mul_lo_u32 v0, v10, s0
	v_add_u32_e32 v12, 0xfffffbe0, v104
	v_lshl_add_u32 v13, v2, 2, v0
	s_mov_b64 s[40:41], 0
	s_branch .LBB0_668
